# v16 + P7 EpiDown first part: x1 loads issued four row groups ahead with counted waits (row-sum atomics no longer drained per group)
# baseline (speedup 1.0000x reference)
; #define LAS __attribute__((address_space(3)))
;     __device__ __forceinline__ void operator()(pg8::f32x4 (&acc)[2][2][4][2], const Unit& u, int wr, int wc, int fr, int fq) const {
;     ...
;             for (int m = 0; m < 4; ++m) { const int rg = row0 + ai * HALF + m * 16; float s0 = 0.f, s1 = 0.f;
; #pragma unroll
;                 for (int bj = 0; bj < 2; ++bj) { *(LAS pg8::f32x4*)epi_slot(W, fr, 2 * fq) = acc[ai][bj][m][0]; *(LAS pg8::f32x4*)epi_slot(W, fr, 2 * fq + 1) = acc[ai][bj][m][1];
; #pragma unroll
;                     for (int p = 0; p < 2; ++p) { const size_t off = (size_t)(rg + 8 * p + rr) * DM + cbase + bj * HALF; const v2u xw = *(const v2u*)(X1 + off);
;                         const pg8::f32x4 x2 = (pg8::f32x4){bflo(xw.x), bfhi(xw.x), bflo(xw.y), bfhi(xw.y)} + *(const LAS pg8::f32x4*)epi_slot(W, 8 * p + rr, sl);
;                         const float q = (x2[0] * x2[0] + x2[1] * x2[1]) + (x2[2] * x2[2] + x2[3] * x2[3]); if (p == 0) s0 += q; else s1 += q;
;                         acc[ai][bj][m][p] = x2; } }
;                 s0 += __shfl_xor(s0, 1); s1 += __shfl_xor(s1, 1); s0 += __shfl_xor(s0, 2); s1 += __shfl_xor(s1, 2); s0 += __shfl_xor(s0, 4); s1 += __shfl_xor(s1, 4);
;                 if (sl == 0) { __hip_atomic_fetch_add(SS2 + rg + rr, s0, __ATOMIC_RELAXED, __HIP_MEMORY_SCOPE_AGENT); __hip_atomic_fetch_add(SS2 + rg + 8 + rr, s1, __ATOMIC_RELAXED, __HIP_MEMORY_SCOPE_AGENT); }
.LBB0_1071:
	s_lshl_b32 s5, s64, 8
	s_add_i32 s30, s5, s44
	s_ashr_i32 s5, s4, 31
	v_or_b32_e32 v152, s30, v166
	s_lshl_b64 s[4:5], s[4:5], 8
	v_ashrrev_i32_e32 v153, 31, v152
	v_mov_b32_e32 v151, s5
	v_or_b32_e32 v150, s4, v138
	v_lshlrev_b64 v[156:157], 11, v[152:153]
	v_lshl_add_u64 v[156:157], s[46:47], 0, v[156:157]
	v_lshlrev_b64 v[158:159], 1, v[150:151]
	v_lshl_add_u64 v[156:157], v[156:157], 0, v[158:159]
	v_lshlrev_b32_e32 v226, 11, v166
	v_add_u32_e32 v226, v226, v158
	v_add_u32_e32 v227, 0x4000, v226
	s_lshl_b32 s36, s30, 11
	s_add_u32 s36, s46, s36
	s_addc_u32 s37, s47, 0
	global_load_dwordx2 v[194:195], v226, s[36:37]
	global_load_dwordx2 v[196:197], v227, s[36:37]
	global_load_dwordx2 v[198:199], v227, s[36:37] offset:256
	global_load_dwordx2 v[200:201], v226, s[36:37] offset:256
	s_add_i32 s36, s30, 16
	s_lshl_b32 s36, s36, 11
	s_add_u32 s36, s46, s36
	s_addc_u32 s37, s47, 0
	global_load_dwordx2 v[202:203], v226, s[36:37]
	global_load_dwordx2 v[204:205], v227, s[36:37]
	global_load_dwordx2 v[206:207], v227, s[36:37] offset:256
	global_load_dwordx2 v[208:209], v226, s[36:37] offset:256
	s_add_i32 s36, s30, 32
	s_lshl_b32 s36, s36, 11
	s_add_u32 s36, s46, s36
	s_addc_u32 s37, s47, 0
	global_load_dwordx2 v[210:211], v226, s[36:37]
	global_load_dwordx2 v[212:213], v227, s[36:37]
	global_load_dwordx2 v[214:215], v227, s[36:37] offset:256
	global_load_dwordx2 v[216:217], v226, s[36:37] offset:256
	s_add_i32 s36, s30, 48
	s_lshl_b32 s36, s36, 11
	s_add_u32 s36, s46, s36
	s_addc_u32 s37, s47, 0
	global_load_dwordx2 v[218:219], v226, s[36:37]
	global_load_dwordx2 v[220:221], v227, s[36:37]
	global_load_dwordx2 v[222:223], v227, s[36:37] offset:256
	global_load_dwordx2 v[224:225], v226, s[36:37] offset:256
	v_or_b32_e32 v156, 8, v152
	v_ashrrev_i32_e32 v157, 31, v156
	v_lshlrev_b64 v[160:161], 11, v[156:157]
	v_lshl_add_u64 v[160:161], s[46:47], 0, v[160:161]
	v_lshl_add_u64 v[160:161], v[160:161], 0, v[158:159]
	v_and_b32_e32 v160, 64, v170
	ds_write_b128 v173, v[126:129]
	ds_write_b128 v174, v[122:125]
	v_add_u32_e32 v189, 64, v160
	ds_read_b128 v[122:125], v175
	ds_read_b128 v[160:163], v175 offset:1024
	ds_write_b128 v173, v[118:121]
	ds_write_b128 v174, v[114:117]
	v_xor_b32_e32 v176, 1, v170
	ds_read_b128 v[114:117], v175
	ds_read_b128 v[178:181], v175 offset:1024
	v_cmp_lt_i32_e32 vcc, v176, v189
	v_xor_b32_e32 v177, 2, v170
	v_xor_b32_e32 v188, 4, v170
	v_cndmask_b32_e32 v118, v170, v176, vcc
	v_lshlrev_b32_e32 v176, 2, v118
	v_cmp_lt_i32_e32 vcc, v177, v189
	s_waitcnt vmcnt(12)
	v_lshlrev_b32_e32 v118, 16, v194
	v_and_b32_e32 v119, 0xffff0000, v194
	v_lshlrev_b32_e32 v120, 16, v195
	v_and_b32_e32 v121, 0xffff0000, v195
	v_lshlrev_b32_e32 v126, 16, v200
	v_and_b32_e32 v127, 0xffff0000, v200
	v_lshlrev_b32_e32 v164, 16, v201
	v_and_b32_e32 v165, 0xffff0000, v201
	s_waitcnt lgkmcnt(5)
	v_pk_add_f32 v[124:125], v[124:125], v[120:121]
	v_pk_add_f32 v[128:129], v[122:123], v[118:119]
	v_lshlrev_b32_e32 v118, 16, v196
	v_and_b32_e32 v119, 0xffff0000, v196
	v_lshlrev_b32_e32 v120, 16, v197
	v_and_b32_e32 v121, 0xffff0000, v197
	s_waitcnt lgkmcnt(1)
	v_pk_add_f32 v[122:123], v[116:117], v[164:165]
	v_pk_add_f32 v[126:127], v[114:115], v[126:127]
	v_lshlrev_b32_e32 v164, 16, v198
	v_and_b32_e32 v165, 0xffff0000, v198
	v_lshlrev_b32_e32 v114, 16, v199
	v_and_b32_e32 v115, 0xffff0000, v199
	s_add_i32 s36, s30, 128
	s_lshl_b32 s36, s36, 11
	s_add_u32 s36, s46, s36
	s_addc_u32 s37, s47, 0
	global_load_dwordx2 v[194:195], v226, s[36:37]
	global_load_dwordx2 v[196:197], v227, s[36:37]
	global_load_dwordx2 v[198:199], v227, s[36:37] offset:256
	global_load_dwordx2 v[200:201], v226, s[36:37] offset:256
	v_pk_add_f32 v[116:117], v[162:163], v[120:121]
	v_pk_add_f32 v[118:119], v[160:161], v[118:119]
	s_waitcnt lgkmcnt(0)
	v_pk_add_f32 v[114:115], v[180:181], v[114:115]
	v_pk_add_f32 v[120:121], v[178:179], v[164:165]
	v_mul_f32_e32 v182, v129, v129
	v_mul_f32_e32 v183, v125, v125
	v_mul_f32_e32 v160, v127, v127
	v_mul_f32_e32 v161, v123, v123
	v_mul_f32_e32 v162, v119, v119
	v_mul_f32_e32 v163, v117, v117
	v_mul_f32_e32 v164, v121, v121
	v_mul_f32_e32 v165, v115, v115
	v_fmac_f32_e32 v182, v128, v128
	v_fmac_f32_e32 v183, v124, v124
	v_fmac_f32_e32 v160, v126, v126
	v_fmac_f32_e32 v161, v122, v122
	v_fmac_f32_e32 v162, v118, v118
	v_fmac_f32_e32 v163, v116, v116
	v_fmac_f32_e32 v164, v120, v120
	v_fmac_f32_e32 v165, v114, v114
	v_add_f32_e32 v178, v182, v183
	v_add_f32_e32 v160, v160, v161
	v_add_f32_e32 v161, v162, v163
	v_add_f32_e32 v162, v164, v165
	v_add_f32_e32 v160, v178, v160
	v_add_f32_e32 v161, v161, v162
	ds_bpermute_b32 v162, v176, v160
	ds_bpermute_b32 v163, v176, v161
	v_cndmask_b32_e32 v164, v170, v177, vcc
	v_lshlrev_b32_e32 v177, 2, v164
	v_cmp_lt_i32_e32 vcc, v188, v189
	s_waitcnt lgkmcnt(1)
	v_add_f32_e32 v160, v160, v162
	s_waitcnt lgkmcnt(0)
	v_add_f32_e32 v161, v161, v163
	ds_bpermute_b32 v162, v177, v160
	ds_bpermute_b32 v163, v177, v161
	v_cndmask_b32_e32 v164, v170, v188, vcc
	v_lshlrev_b32_e32 v178, 2, v164
	s_waitcnt lgkmcnt(1)
	v_add_f32_e32 v160, v160, v162
	s_waitcnt lgkmcnt(0)
	v_add_f32_e32 v161, v161, v163
	ds_bpermute_b32 v162, v178, v160
	ds_bpermute_b32 v163, v178, v161
	s_and_saveexec_b64 s[4:5], s[6:7]
	s_cbranch_execz .LBB0_1073
	s_ashr_i32 s31, s30, 31
	s_waitcnt lgkmcnt(0)
	v_add_f32_e32 v163, v161, v163
	v_add_f32_e32 v162, v160, v162
	v_lshl_add_u64 v[160:161], s[30:31], 2, v[140:141]
	global_atomic_add_f32 v[160:161], v162, off
	global_atomic_add_f32 v[160:161], v163, off offset:32
; #define LAS __attribute__((address_space(3)))
;     __device__ __forceinline__ void operator()(pg8::f32x4 (&acc)[2][2][4][2], const Unit& u, int wr, int wc, int fr, int fq) const {
;     ...
;             for (int m = 0; m < 4; ++m) { const int rg = row0 + ai * HALF + m * 16; float s0 = 0.f, s1 = 0.f;
; #pragma unroll
;                 for (int bj = 0; bj < 2; ++bj) { *(LAS pg8::f32x4*)epi_slot(W, fr, 2 * fq) = acc[ai][bj][m][0]; *(LAS pg8::f32x4*)epi_slot(W, fr, 2 * fq + 1) = acc[ai][bj][m][1];
; #pragma unroll
;                     for (int p = 0; p < 2; ++p) { const size_t off = (size_t)(rg + 8 * p + rr) * DM + cbase + bj * HALF; const v2u xw = *(const v2u*)(X1 + off);
;                         const pg8::f32x4 x2 = (pg8::f32x4){bflo(xw.x), bfhi(xw.x), bflo(xw.y), bfhi(xw.y)} + *(const LAS pg8::f32x4*)epi_slot(W, 8 * p + rr, sl);
;                         const float q = (x2[0] * x2[0] + x2[1] * x2[1]) + (x2[2] * x2[2] + x2[3] * x2[3]); if (p == 0) s0 += q; else s1 += q;
;                         acc[ai][bj][m][p] = x2; } }
;                 s0 += __shfl_xor(s0, 1); s1 += __shfl_xor(s1, 1); s0 += __shfl_xor(s0, 2); s1 += __shfl_xor(s1, 2); s0 += __shfl_xor(s0, 4); s1 += __shfl_xor(s1, 4);
;                 if (sl == 0) { __hip_atomic_fetch_add(SS2 + rg + rr, s0, __ATOMIC_RELAXED, __HIP_MEMORY_SCOPE_AGENT); __hip_atomic_fetch_add(SS2 + rg + 8 + rr, s1, __ATOMIC_RELAXED, __HIP_MEMORY_SCOPE_AGENT); }
.LBB0_1073:
	s_or_b64 exec, exec, s[4:5]
	s_or_b32 s4, s30, 16
	v_or_b32_e32 v160, s4, v166
	v_ashrrev_i32_e32 v161, 31, v160
	s_waitcnt lgkmcnt(0)
	v_lshlrev_b64 v[162:163], 11, v[160:161]
	v_or_b32_e32 v160, 8, v160
	v_ashrrev_i32_e32 v161, 31, v160
	v_lshl_add_u64 v[162:163], s[46:47], 0, v[162:163]
	v_lshlrev_b64 v[160:161], 11, v[160:161]
	v_lshl_add_u64 v[162:163], v[162:163], 0, v[158:159]
	v_lshl_add_u64 v[160:161], s[46:47], 0, v[160:161]
	v_lshl_add_u64 v[160:161], v[160:161], 0, v[158:159]
	ds_write_b128 v173, v[110:113]
	ds_write_b128 v174, v[106:109]
	ds_read_b128 v[108:111], v175
	ds_read_b128 v[160:163], v175 offset:1024
	ds_write_b128 v173, v[102:105]
	ds_write_b128 v174, v[98:101]
	ds_read_b128 v[180:183], v175
	ds_read_b128 v[184:187], v175 offset:1024
	s_waitcnt vmcnt(14)
	v_lshlrev_b32_e32 v98, 16, v202
	v_and_b32_e32 v99, 0xffff0000, v202
	v_lshlrev_b32_e32 v100, 16, v203
	v_and_b32_e32 v101, 0xffff0000, v203
	s_waitcnt lgkmcnt(5)
	v_pk_add_f32 v[106:107], v[110:111], v[100:101]
	v_pk_add_f32 v[108:109], v[108:109], v[98:99]
	s_waitcnt vmcnt(14)
	v_lshlrev_b32_e32 v98, 16, v204
	v_and_b32_e32 v99, 0xffff0000, v204
	v_lshlrev_b32_e32 v100, 16, v205
	v_and_b32_e32 v101, 0xffff0000, v205
	s_waitcnt vmcnt(14)
	v_lshlrev_b32_e32 v104, 16, v208
	v_and_b32_e32 v105, 0xffff0000, v208
	v_lshlrev_b32_e32 v110, 16, v209
	v_and_b32_e32 v111, 0xffff0000, v209
	v_lshlrev_b32_e32 v164, 16, v206
	v_and_b32_e32 v165, 0xffff0000, v206
	v_lshlrev_b32_e32 v188, 16, v207
	v_and_b32_e32 v189, 0xffff0000, v207
	s_add_i32 s36, s30, 144
	s_lshl_b32 s36, s36, 11
	s_add_u32 s36, s46, s36
	s_addc_u32 s37, s47, 0
	global_load_dwordx2 v[202:203], v226, s[36:37]
	global_load_dwordx2 v[204:205], v227, s[36:37]
	global_load_dwordx2 v[206:207], v227, s[36:37] offset:256
	global_load_dwordx2 v[208:209], v226, s[36:37] offset:256
	s_waitcnt lgkmcnt(4)
	v_pk_add_f32 v[100:101], v[162:163], v[100:101]
	v_pk_add_f32 v[102:103], v[160:161], v[98:99]
	s_waitcnt lgkmcnt(1)
	v_pk_add_f32 v[110:111], v[182:183], v[110:111]
	v_pk_add_f32 v[112:113], v[180:181], v[104:105]
	s_waitcnt lgkmcnt(0)
	v_pk_add_f32 v[98:99], v[186:187], v[188:189]
	v_pk_add_f32 v[104:105], v[184:185], v[164:165]
	v_mul_f32_e32 v179, v109, v109
	v_mul_f32_e32 v190, v107, v107
	v_mul_f32_e32 v160, v103, v103
	v_mul_f32_e32 v161, v101, v101
	v_mul_f32_e32 v162, v113, v113
	v_mul_f32_e32 v163, v111, v111
	v_mul_f32_e32 v164, v105, v105
	v_mul_f32_e32 v165, v99, v99
	v_fmac_f32_e32 v179, v108, v108
	v_fmac_f32_e32 v190, v106, v106
	v_fmac_f32_e32 v160, v102, v102
	v_fmac_f32_e32 v161, v100, v100
	v_fmac_f32_e32 v162, v112, v112
	v_fmac_f32_e32 v163, v110, v110
	v_fmac_f32_e32 v164, v104, v104
	v_fmac_f32_e32 v165, v98, v98
	v_add_f32_e32 v179, v179, v190
	v_add_f32_e32 v160, v160, v161
	v_add_f32_e32 v161, v162, v163
	v_add_f32_e32 v162, v164, v165
	v_add_f32_e32 v161, v179, v161
	v_add_f32_e32 v160, v160, v162
	ds_bpermute_b32 v162, v176, v161
	ds_bpermute_b32 v163, v176, v160
	s_waitcnt lgkmcnt(1)
	v_add_f32_e32 v161, v161, v162
	s_waitcnt lgkmcnt(0)
	v_add_f32_e32 v162, v160, v163
	ds_bpermute_b32 v160, v177, v161
	ds_bpermute_b32 v163, v177, v162
	s_waitcnt lgkmcnt(1)
	v_add_f32_e32 v160, v161, v160
	s_waitcnt lgkmcnt(0)
	v_add_f32_e32 v161, v162, v163
	ds_bpermute_b32 v162, v178, v160
	ds_bpermute_b32 v163, v178, v161
	s_and_saveexec_b64 s[34:35], s[6:7]
	s_cbranch_execz .LBB0_1075
	s_ashr_i32 s5, s4, 31
	s_waitcnt lgkmcnt(0)
	v_add_f32_e32 v163, v161, v163
	v_add_f32_e32 v162, v160, v162
	v_lshl_add_u64 v[160:161], s[4:5], 2, v[140:141]
	global_atomic_add_f32 v[160:161], v162, off
	global_atomic_add_f32 v[160:161], v163, off offset:32
.LBB0_1075:
	s_or_b64 exec, exec, s[34:35]
	s_or_b32 s4, s30, 32
	v_or_b32_e32 v160, s4, v166
	v_ashrrev_i32_e32 v161, 31, v160
	s_waitcnt lgkmcnt(0)
	v_lshlrev_b64 v[162:163], 11, v[160:161]
	v_or_b32_e32 v160, 8, v160
	v_ashrrev_i32_e32 v161, 31, v160
	v_lshl_add_u64 v[162:163], s[46:47], 0, v[162:163]
	v_lshlrev_b64 v[160:161], 11, v[160:161]
	v_lshl_add_u64 v[162:163], v[162:163], 0, v[158:159]
	v_lshl_add_u64 v[160:161], s[46:47], 0, v[160:161]
	v_lshl_add_u64 v[160:161], v[160:161], 0, v[158:159]
	ds_write_b128 v173, v[94:97]
	ds_write_b128 v174, v[90:93]
	ds_read_b128 v[92:95], v175
	ds_read_b128 v[160:163], v175 offset:1024
	ds_write_b128 v173, v[86:89]
	ds_write_b128 v174, v[82:85]
	ds_read_b128 v[180:183], v175
	ds_read_b128 v[184:187], v175 offset:1024
	s_waitcnt vmcnt(16)
	v_lshlrev_b32_e32 v82, 16, v210
	v_and_b32_e32 v83, 0xffff0000, v210
	v_lshlrev_b32_e32 v84, 16, v211
	v_and_b32_e32 v85, 0xffff0000, v211
	s_waitcnt lgkmcnt(5)
	v_pk_add_f32 v[90:91], v[94:95], v[84:85]
	v_pk_add_f32 v[92:93], v[92:93], v[82:83]
	s_waitcnt vmcnt(16)
	v_lshlrev_b32_e32 v82, 16, v212
	v_and_b32_e32 v83, 0xffff0000, v212
	v_lshlrev_b32_e32 v84, 16, v213
	v_and_b32_e32 v85, 0xffff0000, v213
	s_waitcnt vmcnt(16)
	v_lshlrev_b32_e32 v88, 16, v216
	v_and_b32_e32 v89, 0xffff0000, v216
	v_lshlrev_b32_e32 v94, 16, v217
	v_and_b32_e32 v95, 0xffff0000, v217
	v_lshlrev_b32_e32 v164, 16, v214
	v_and_b32_e32 v165, 0xffff0000, v214
	v_lshlrev_b32_e32 v188, 16, v215
	v_and_b32_e32 v189, 0xffff0000, v215
	s_add_i32 s36, s30, 160
	s_lshl_b32 s36, s36, 11
	s_add_u32 s36, s46, s36
	s_addc_u32 s37, s47, 0
	global_load_dwordx2 v[210:211], v226, s[36:37]
	global_load_dwordx2 v[212:213], v227, s[36:37]
	global_load_dwordx2 v[214:215], v227, s[36:37] offset:256
	global_load_dwordx2 v[216:217], v226, s[36:37] offset:256
	s_waitcnt lgkmcnt(4)
	v_pk_add_f32 v[84:85], v[162:163], v[84:85]
	v_pk_add_f32 v[86:87], v[160:161], v[82:83]
	s_waitcnt lgkmcnt(1)
	v_pk_add_f32 v[94:95], v[182:183], v[94:95]
	v_pk_add_f32 v[96:97], v[180:181], v[88:89]
	s_waitcnt lgkmcnt(0)
	v_pk_add_f32 v[82:83], v[186:187], v[188:189]
	v_pk_add_f32 v[88:89], v[184:185], v[164:165]
	v_mul_f32_e32 v179, v93, v93
	v_mul_f32_e32 v190, v91, v91
	v_mul_f32_e32 v160, v87, v87
	v_mul_f32_e32 v161, v85, v85
	v_mul_f32_e32 v162, v97, v97
	v_mul_f32_e32 v163, v95, v95
	v_mul_f32_e32 v164, v89, v89
	v_mul_f32_e32 v165, v83, v83
	v_fmac_f32_e32 v179, v92, v92
	v_fmac_f32_e32 v190, v90, v90
	v_fmac_f32_e32 v160, v86, v86
	v_fmac_f32_e32 v161, v84, v84
	v_fmac_f32_e32 v162, v96, v96
	v_fmac_f32_e32 v163, v94, v94
	v_fmac_f32_e32 v164, v88, v88
	v_fmac_f32_e32 v165, v82, v82
	v_add_f32_e32 v179, v179, v190
	v_add_f32_e32 v160, v160, v161
	v_add_f32_e32 v161, v162, v163
	v_add_f32_e32 v162, v164, v165
	v_add_f32_e32 v161, v179, v161
	v_add_f32_e32 v160, v160, v162
	ds_bpermute_b32 v162, v176, v161
	ds_bpermute_b32 v163, v176, v160
	s_waitcnt lgkmcnt(1)
	v_add_f32_e32 v161, v161, v162
	s_waitcnt lgkmcnt(0)
	v_add_f32_e32 v162, v160, v163
	ds_bpermute_b32 v160, v177, v161
	ds_bpermute_b32 v163, v177, v162
	s_waitcnt lgkmcnt(1)
	v_add_f32_e32 v160, v161, v160
	s_waitcnt lgkmcnt(0)
	v_add_f32_e32 v161, v162, v163
	ds_bpermute_b32 v162, v178, v160
	ds_bpermute_b32 v163, v178, v161
	s_and_saveexec_b64 s[34:35], s[6:7]
	s_cbranch_execz .LBB0_1077
; #define LAS __attribute__((address_space(3)))
;     __device__ __forceinline__ void operator()(pg8::f32x4 (&acc)[2][2][4][2], const Unit& u, int wr, int wc, int fr, int fq) const {
;     ...
;             for (int m = 0; m < 4; ++m) { const int rg = row0 + ai * HALF + m * 16; float s0 = 0.f, s1 = 0.f;
; #pragma unroll
;                 for (int bj = 0; bj < 2; ++bj) { *(LAS pg8::f32x4*)epi_slot(W, fr, 2 * fq) = acc[ai][bj][m][0]; *(LAS pg8::f32x4*)epi_slot(W, fr, 2 * fq + 1) = acc[ai][bj][m][1];
; #pragma unroll
;                     for (int p = 0; p < 2; ++p) { const size_t off = (size_t)(rg + 8 * p + rr) * DM + cbase + bj * HALF; const v2u xw = *(const v2u*)(X1 + off);
;                         const pg8::f32x4 x2 = (pg8::f32x4){bflo(xw.x), bfhi(xw.x), bflo(xw.y), bfhi(xw.y)} + *(const LAS pg8::f32x4*)epi_slot(W, 8 * p + rr, sl);
;                         const float q = (x2[0] * x2[0] + x2[1] * x2[1]) + (x2[2] * x2[2] + x2[3] * x2[3]); if (p == 0) s0 += q; else s1 += q;
;                         acc[ai][bj][m][p] = x2; } }
;                 s0 += __shfl_xor(s0, 1); s1 += __shfl_xor(s1, 1); s0 += __shfl_xor(s0, 2); s1 += __shfl_xor(s1, 2); s0 += __shfl_xor(s0, 4); s1 += __shfl_xor(s1, 4);
;                 if (sl == 0) { __hip_atomic_fetch_add(SS2 + rg + rr, s0, __ATOMIC_RELAXED, __HIP_MEMORY_SCOPE_AGENT); __hip_atomic_fetch_add(SS2 + rg + 8 + rr, s1, __ATOMIC_RELAXED, __HIP_MEMORY_SCOPE_AGENT); }
	s_ashr_i32 s5, s4, 31
	s_waitcnt lgkmcnt(0)
	v_add_f32_e32 v163, v161, v163
	v_add_f32_e32 v162, v160, v162
	v_lshl_add_u64 v[160:161], s[4:5], 2, v[140:141]
	global_atomic_add_f32 v[160:161], v162, off
	global_atomic_add_f32 v[160:161], v163, off offset:32
.LBB0_1077:
	s_or_b64 exec, exec, s[34:35]
	s_or_b32 s4, s30, 48
	v_or_b32_e32 v160, s4, v166
	v_ashrrev_i32_e32 v161, 31, v160
	s_waitcnt lgkmcnt(0)
	v_lshlrev_b64 v[162:163], 11, v[160:161]
	v_or_b32_e32 v160, 8, v160
	v_ashrrev_i32_e32 v161, 31, v160
	v_lshl_add_u64 v[162:163], s[46:47], 0, v[162:163]
	v_lshlrev_b64 v[160:161], 11, v[160:161]
	v_lshl_add_u64 v[162:163], v[162:163], 0, v[158:159]
	v_lshl_add_u64 v[160:161], s[46:47], 0, v[160:161]
	v_lshl_add_u64 v[160:161], v[160:161], 0, v[158:159]
	ds_write_b128 v173, v[78:81]
	ds_write_b128 v174, v[74:77]
	ds_read_b128 v[76:79], v175
	ds_read_b128 v[160:163], v175 offset:1024
	ds_write_b128 v173, v[70:73]
	ds_write_b128 v174, v[66:69]
	ds_read_b128 v[180:183], v175
	ds_read_b128 v[184:187], v175 offset:1024
	s_waitcnt vmcnt(18)
	v_lshlrev_b32_e32 v66, 16, v218
	v_and_b32_e32 v67, 0xffff0000, v218
	v_lshlrev_b32_e32 v68, 16, v219
	v_and_b32_e32 v69, 0xffff0000, v219
	s_waitcnt lgkmcnt(5)
	v_pk_add_f32 v[74:75], v[78:79], v[68:69]
	v_pk_add_f32 v[76:77], v[76:77], v[66:67]
	s_waitcnt vmcnt(18)
	v_lshlrev_b32_e32 v66, 16, v220
	v_and_b32_e32 v67, 0xffff0000, v220
	v_lshlrev_b32_e32 v68, 16, v221
	v_and_b32_e32 v69, 0xffff0000, v221
	s_waitcnt vmcnt(18)
	v_lshlrev_b32_e32 v72, 16, v224
	v_and_b32_e32 v73, 0xffff0000, v224
	v_lshlrev_b32_e32 v78, 16, v225
	v_and_b32_e32 v79, 0xffff0000, v225
	v_lshlrev_b32_e32 v164, 16, v222
	v_and_b32_e32 v165, 0xffff0000, v222
	v_lshlrev_b32_e32 v188, 16, v223
	v_and_b32_e32 v189, 0xffff0000, v223
	s_add_i32 s36, s30, 176
	s_lshl_b32 s36, s36, 11
	s_add_u32 s36, s46, s36
	s_addc_u32 s37, s47, 0
	global_load_dwordx2 v[218:219], v226, s[36:37]
	global_load_dwordx2 v[220:221], v227, s[36:37]
	global_load_dwordx2 v[222:223], v227, s[36:37] offset:256
	global_load_dwordx2 v[224:225], v226, s[36:37] offset:256
	s_waitcnt lgkmcnt(4)
	v_pk_add_f32 v[68:69], v[162:163], v[68:69]
	v_pk_add_f32 v[70:71], v[160:161], v[66:67]
	s_waitcnt lgkmcnt(1)
	v_pk_add_f32 v[78:79], v[182:183], v[78:79]
	v_pk_add_f32 v[80:81], v[180:181], v[72:73]
	s_waitcnt lgkmcnt(0)
	v_pk_add_f32 v[66:67], v[186:187], v[188:189]
	v_pk_add_f32 v[72:73], v[184:185], v[164:165]
	v_mul_f32_e32 v179, v77, v77
	v_mul_f32_e32 v190, v75, v75
	v_mul_f32_e32 v160, v71, v71
	v_mul_f32_e32 v161, v69, v69
	v_mul_f32_e32 v162, v81, v81
	v_mul_f32_e32 v163, v79, v79
	v_mul_f32_e32 v164, v73, v73
	v_mul_f32_e32 v165, v67, v67
	v_fmac_f32_e32 v179, v76, v76
	v_fmac_f32_e32 v190, v74, v74
	v_fmac_f32_e32 v160, v70, v70
	v_fmac_f32_e32 v161, v68, v68
	v_fmac_f32_e32 v162, v80, v80
	v_fmac_f32_e32 v163, v78, v78
	v_fmac_f32_e32 v164, v72, v72
	v_fmac_f32_e32 v165, v66, v66
	v_add_f32_e32 v179, v179, v190
	v_add_f32_e32 v160, v160, v161
	v_add_f32_e32 v161, v162, v163
	v_add_f32_e32 v162, v164, v165
	v_add_f32_e32 v161, v179, v161
	v_add_f32_e32 v160, v160, v162
	ds_bpermute_b32 v162, v176, v161
	ds_bpermute_b32 v163, v176, v160
	s_waitcnt lgkmcnt(1)
	v_add_f32_e32 v161, v161, v162
	s_waitcnt lgkmcnt(0)
	v_add_f32_e32 v162, v160, v163
	ds_bpermute_b32 v160, v177, v161
	ds_bpermute_b32 v163, v177, v162
	s_waitcnt lgkmcnt(1)
	v_add_f32_e32 v160, v161, v160
	s_waitcnt lgkmcnt(0)
	v_add_f32_e32 v161, v162, v163
	ds_bpermute_b32 v162, v178, v160
	ds_bpermute_b32 v163, v178, v161
	s_and_saveexec_b64 s[34:35], s[6:7]
	s_cbranch_execz .LBB0_1079
	s_ashr_i32 s5, s4, 31
	s_waitcnt lgkmcnt(0)
	v_add_f32_e32 v163, v161, v163
	v_add_f32_e32 v162, v160, v162
	v_lshl_add_u64 v[160:161], s[4:5], 2, v[140:141]
	global_atomic_add_f32 v[160:161], v162, off
	global_atomic_add_f32 v[160:161], v163, off offset:32
.LBB0_1079:
	s_or_b64 exec, exec, s[34:35]
	s_add_i32 s4, s30, 0x80
	v_or_b32_e32 v160, s4, v166
	v_ashrrev_i32_e32 v161, 31, v160
	s_waitcnt lgkmcnt(0)
	v_lshlrev_b64 v[162:163], 11, v[160:161]
	v_or_b32_e32 v160, 8, v160
	v_ashrrev_i32_e32 v161, 31, v160
	v_lshl_add_u64 v[162:163], s[46:47], 0, v[162:163]
	v_lshlrev_b64 v[160:161], 11, v[160:161]
	v_lshl_add_u64 v[162:163], v[162:163], 0, v[158:159]
	v_lshl_add_u64 v[160:161], s[46:47], 0, v[160:161]
	v_lshl_add_u64 v[160:161], v[160:161], 0, v[158:159]
	ds_write_b128 v173, v[62:65]
	ds_write_b128 v174, v[58:61]
	ds_read_b128 v[60:63], v175
	ds_read_b128 v[160:163], v175 offset:1024
	ds_write_b128 v173, v[54:57]
	ds_write_b128 v174, v[50:53]
	ds_read_b128 v[180:183], v175
	ds_read_b128 v[184:187], v175 offset:1024
	s_waitcnt vmcnt(20)
	v_lshlrev_b32_e32 v50, 16, v194
	v_and_b32_e32 v51, 0xffff0000, v194
	v_lshlrev_b32_e32 v52, 16, v195
	v_and_b32_e32 v53, 0xffff0000, v195
	s_waitcnt lgkmcnt(5)
	v_pk_add_f32 v[58:59], v[62:63], v[52:53]
	v_pk_add_f32 v[60:61], v[60:61], v[50:51]
	s_waitcnt vmcnt(20)
	v_lshlrev_b32_e32 v50, 16, v196
	v_and_b32_e32 v51, 0xffff0000, v196
	v_lshlrev_b32_e32 v52, 16, v197
	v_and_b32_e32 v53, 0xffff0000, v197
	s_waitcnt vmcnt(20)
	v_lshlrev_b32_e32 v56, 16, v200
	v_and_b32_e32 v57, 0xffff0000, v200
	v_lshlrev_b32_e32 v62, 16, v201
	v_and_b32_e32 v63, 0xffff0000, v201
	v_lshlrev_b32_e32 v164, 16, v198
	v_and_b32_e32 v165, 0xffff0000, v198
	v_lshlrev_b32_e32 v188, 16, v199
	v_and_b32_e32 v189, 0xffff0000, v199
	s_waitcnt lgkmcnt(4)
	v_pk_add_f32 v[52:53], v[162:163], v[52:53]
	v_pk_add_f32 v[54:55], v[160:161], v[50:51]
	s_waitcnt lgkmcnt(1)
	v_pk_add_f32 v[62:63], v[182:183], v[62:63]
	v_pk_add_f32 v[64:65], v[180:181], v[56:57]
	s_waitcnt lgkmcnt(0)
	v_pk_add_f32 v[50:51], v[186:187], v[188:189]
	v_pk_add_f32 v[56:57], v[184:185], v[164:165]
	v_mul_f32_e32 v179, v61, v61
	v_mul_f32_e32 v190, v59, v59
	v_mul_f32_e32 v160, v55, v55
	v_mul_f32_e32 v161, v53, v53
	v_mul_f32_e32 v162, v65, v65
	v_mul_f32_e32 v163, v63, v63
	v_mul_f32_e32 v164, v57, v57
	v_mul_f32_e32 v165, v51, v51
	v_fmac_f32_e32 v179, v60, v60
	v_fmac_f32_e32 v190, v58, v58
	v_fmac_f32_e32 v160, v54, v54
	v_fmac_f32_e32 v161, v52, v52
	v_fmac_f32_e32 v162, v64, v64
	v_fmac_f32_e32 v163, v62, v62
	v_fmac_f32_e32 v164, v56, v56
	v_fmac_f32_e32 v165, v50, v50
	v_add_f32_e32 v179, v179, v190
	v_add_f32_e32 v160, v160, v161
	v_add_f32_e32 v161, v162, v163
	v_add_f32_e32 v162, v164, v165
	v_add_f32_e32 v161, v179, v161
	v_add_f32_e32 v160, v160, v162
	ds_bpermute_b32 v162, v176, v161
	ds_bpermute_b32 v163, v176, v160
	s_waitcnt lgkmcnt(1)
	v_add_f32_e32 v161, v161, v162
	s_waitcnt lgkmcnt(0)
	v_add_f32_e32 v162, v160, v163
	ds_bpermute_b32 v160, v177, v161
	ds_bpermute_b32 v163, v177, v162
	s_waitcnt lgkmcnt(1)
	v_add_f32_e32 v160, v161, v160
	s_waitcnt lgkmcnt(0)
	v_add_f32_e32 v161, v162, v163
	ds_bpermute_b32 v162, v178, v160
	ds_bpermute_b32 v163, v178, v161
	s_and_saveexec_b64 s[34:35], s[6:7]
	s_cbranch_execz .LBB0_1081
; #define LAS __attribute__((address_space(3)))
;     __device__ __forceinline__ void operator()(pg8::f32x4 (&acc)[2][2][4][2], const Unit& u, int wr, int wc, int fr, int fq) const {
;     ...
;             for (int m = 0; m < 4; ++m) { const int rg = row0 + ai * HALF + m * 16; float s0 = 0.f, s1 = 0.f;
; #pragma unroll
;                 for (int bj = 0; bj < 2; ++bj) { *(LAS pg8::f32x4*)epi_slot(W, fr, 2 * fq) = acc[ai][bj][m][0]; *(LAS pg8::f32x4*)epi_slot(W, fr, 2 * fq + 1) = acc[ai][bj][m][1];
; #pragma unroll
;                     for (int p = 0; p < 2; ++p) { const size_t off = (size_t)(rg + 8 * p + rr) * DM + cbase + bj * HALF; const v2u xw = *(const v2u*)(X1 + off);
;                         const pg8::f32x4 x2 = (pg8::f32x4){bflo(xw.x), bfhi(xw.x), bflo(xw.y), bfhi(xw.y)} + *(const LAS pg8::f32x4*)epi_slot(W, 8 * p + rr, sl);
;                         const float q = (x2[0] * x2[0] + x2[1] * x2[1]) + (x2[2] * x2[2] + x2[3] * x2[3]); if (p == 0) s0 += q; else s1 += q;
;                         acc[ai][bj][m][p] = x2; } }
;                 s0 += __shfl_xor(s0, 1); s1 += __shfl_xor(s1, 1); s0 += __shfl_xor(s0, 2); s1 += __shfl_xor(s1, 2); s0 += __shfl_xor(s0, 4); s1 += __shfl_xor(s1, 4);
;                 if (sl == 0) { __hip_atomic_fetch_add(SS2 + rg + rr, s0, __ATOMIC_RELAXED, __HIP_MEMORY_SCOPE_AGENT); __hip_atomic_fetch_add(SS2 + rg + 8 + rr, s1, __ATOMIC_RELAXED, __HIP_MEMORY_SCOPE_AGENT); }
	s_ashr_i32 s5, s4, 31
	s_waitcnt lgkmcnt(0)
	v_add_f32_e32 v163, v161, v163
	v_add_f32_e32 v162, v160, v162
	v_lshl_add_u64 v[160:161], s[4:5], 2, v[140:141]
	global_atomic_add_f32 v[160:161], v162, off
	global_atomic_add_f32 v[160:161], v163, off offset:32
.LBB0_1081:
	s_or_b64 exec, exec, s[34:35]
	s_add_i32 s4, s30, 0x90
	v_or_b32_e32 v160, s4, v166
	v_ashrrev_i32_e32 v161, 31, v160
	s_waitcnt lgkmcnt(0)
	v_lshlrev_b64 v[162:163], 11, v[160:161]
	v_or_b32_e32 v160, 8, v160
	v_ashrrev_i32_e32 v161, 31, v160
	v_lshl_add_u64 v[162:163], s[46:47], 0, v[162:163]
	v_lshlrev_b64 v[160:161], 11, v[160:161]
	v_lshl_add_u64 v[162:163], v[162:163], 0, v[158:159]
	v_lshl_add_u64 v[160:161], s[46:47], 0, v[160:161]
	v_lshl_add_u64 v[160:161], v[160:161], 0, v[158:159]
	ds_write_b128 v173, v[46:49]
	ds_write_b128 v174, v[42:45]
	ds_read_b128 v[44:47], v175
	ds_read_b128 v[160:163], v175 offset:1024
	ds_write_b128 v173, v[38:41]
	ds_write_b128 v174, v[34:37]
	ds_read_b128 v[180:183], v175
	ds_read_b128 v[184:187], v175 offset:1024
	s_waitcnt vmcnt(16)
	v_lshlrev_b32_e32 v34, 16, v202
	v_and_b32_e32 v35, 0xffff0000, v202
	v_lshlrev_b32_e32 v36, 16, v203
	v_and_b32_e32 v37, 0xffff0000, v203
	s_waitcnt lgkmcnt(5)
	v_pk_add_f32 v[42:43], v[46:47], v[36:37]
	v_pk_add_f32 v[44:45], v[44:45], v[34:35]
	s_waitcnt vmcnt(16)
	v_lshlrev_b32_e32 v34, 16, v204
	v_and_b32_e32 v35, 0xffff0000, v204
	v_lshlrev_b32_e32 v36, 16, v205
	v_and_b32_e32 v37, 0xffff0000, v205
	s_waitcnt vmcnt(16)
	v_lshlrev_b32_e32 v40, 16, v208
	v_and_b32_e32 v41, 0xffff0000, v208
	v_lshlrev_b32_e32 v46, 16, v209
	v_and_b32_e32 v47, 0xffff0000, v209
	v_lshlrev_b32_e32 v164, 16, v206
	v_and_b32_e32 v165, 0xffff0000, v206
	v_lshlrev_b32_e32 v188, 16, v207
	v_and_b32_e32 v189, 0xffff0000, v207
	s_waitcnt lgkmcnt(4)
	v_pk_add_f32 v[36:37], v[162:163], v[36:37]
	v_pk_add_f32 v[38:39], v[160:161], v[34:35]
	s_waitcnt lgkmcnt(1)
	v_pk_add_f32 v[46:47], v[182:183], v[46:47]
	v_pk_add_f32 v[48:49], v[180:181], v[40:41]
	s_waitcnt lgkmcnt(0)
	v_pk_add_f32 v[34:35], v[186:187], v[188:189]
	v_pk_add_f32 v[40:41], v[184:185], v[164:165]
	v_mul_f32_e32 v179, v45, v45
	v_mul_f32_e32 v190, v43, v43
	v_mul_f32_e32 v160, v39, v39
	v_mul_f32_e32 v161, v37, v37
	v_mul_f32_e32 v162, v49, v49
	v_mul_f32_e32 v163, v47, v47
	v_mul_f32_e32 v164, v41, v41
	v_mul_f32_e32 v165, v35, v35
	v_fmac_f32_e32 v179, v44, v44
	v_fmac_f32_e32 v190, v42, v42
	v_fmac_f32_e32 v160, v38, v38
	v_fmac_f32_e32 v161, v36, v36
	v_fmac_f32_e32 v162, v48, v48
	v_fmac_f32_e32 v163, v46, v46
	v_fmac_f32_e32 v164, v40, v40
	v_fmac_f32_e32 v165, v34, v34
	v_add_f32_e32 v179, v179, v190
	v_add_f32_e32 v160, v160, v161
	v_add_f32_e32 v161, v162, v163
	v_add_f32_e32 v162, v164, v165
	v_add_f32_e32 v161, v179, v161
	v_add_f32_e32 v160, v160, v162
	ds_bpermute_b32 v162, v176, v161
	ds_bpermute_b32 v163, v176, v160
	s_waitcnt lgkmcnt(1)
	v_add_f32_e32 v161, v161, v162
	s_waitcnt lgkmcnt(0)
	v_add_f32_e32 v162, v160, v163
	ds_bpermute_b32 v160, v177, v161
	ds_bpermute_b32 v163, v177, v162
	s_waitcnt lgkmcnt(1)
	v_add_f32_e32 v160, v161, v160
	s_waitcnt lgkmcnt(0)
	v_add_f32_e32 v161, v162, v163
	ds_bpermute_b32 v162, v178, v160
	ds_bpermute_b32 v163, v178, v161
	s_and_saveexec_b64 s[34:35], s[6:7]
	s_cbranch_execz .LBB0_1083
	s_ashr_i32 s5, s4, 31
	s_waitcnt lgkmcnt(0)
	v_add_f32_e32 v163, v161, v163
	v_add_f32_e32 v162, v160, v162
	v_lshl_add_u64 v[160:161], s[4:5], 2, v[140:141]
	global_atomic_add_f32 v[160:161], v162, off
	global_atomic_add_f32 v[160:161], v163, off offset:32
; #define LAS __attribute__((address_space(3)))
;     __device__ __forceinline__ void operator()(pg8::f32x4 (&acc)[2][2][4][2], const Unit& u, int wr, int wc, int fr, int fq) const {
;     ...
; #pragma unroll
;         for (int ai = 0; ai < 2; ++ai)
; #pragma unroll
;             for (int m = 0; m < 4; ++m) { const int rg = row0 + ai * HALF + m * 16; float s0 = 0.f, s1 = 0.f;
; #pragma unroll
;                 for (int bj = 0; bj < 2; ++bj) { *(LAS pg8::f32x4*)epi_slot(W, fr, 2 * fq) = acc[ai][bj][m][0]; *(LAS pg8::f32x4*)epi_slot(W, fr, 2 * fq + 1) = acc[ai][bj][m][1];
; #pragma unroll
;                     for (int p = 0; p < 2; ++p) { const size_t off = (size_t)(rg + 8 * p + rr) * DM + cbase + bj * HALF; const v2u xw = *(const v2u*)(X1 + off);
;                         const pg8::f32x4 x2 = (pg8::f32x4){bflo(xw.x), bfhi(xw.x), bflo(xw.y), bfhi(xw.y)} + *(const LAS pg8::f32x4*)epi_slot(W, 8 * p + rr, sl);
;                         const float q = (x2[0] * x2[0] + x2[1] * x2[1]) + (x2[2] * x2[2] + x2[3] * x2[3]); if (p == 0) s0 += q; else s1 += q;
;                         acc[ai][bj][m][p] = x2; } }
;                 s0 += __shfl_xor(s0, 1); s1 += __shfl_xor(s1, 1); s0 += __shfl_xor(s0, 2); s1 += __shfl_xor(s1, 2); s0 += __shfl_xor(s0, 4); s1 += __shfl_xor(s1, 4);
;                 if (sl == 0) { __hip_atomic_fetch_add(SS2 + rg + rr, s0, __ATOMIC_RELAXED, __HIP_MEMORY_SCOPE_AGENT); __hip_atomic_fetch_add(SS2 + rg + 8 + rr, s1, __ATOMIC_RELAXED, __HIP_MEMORY_SCOPE_AGENT); }
;                 asm volatile("" ::: "memory"); }
.LBB0_1083:
	s_or_b64 exec, exec, s[34:35]
	s_add_i32 s4, s30, 0xa0
	v_or_b32_e32 v160, s4, v166
	v_ashrrev_i32_e32 v161, 31, v160
	s_waitcnt lgkmcnt(0)
	v_lshlrev_b64 v[162:163], 11, v[160:161]
	v_or_b32_e32 v160, 8, v160
	v_ashrrev_i32_e32 v161, 31, v160
	v_lshl_add_u64 v[162:163], s[46:47], 0, v[162:163]
	v_lshlrev_b64 v[160:161], 11, v[160:161]
	v_lshl_add_u64 v[162:163], v[162:163], 0, v[158:159]
	v_lshl_add_u64 v[160:161], s[46:47], 0, v[160:161]
	v_lshl_add_u64 v[160:161], v[160:161], 0, v[158:159]
	ds_write_b128 v173, v[30:33]
	ds_write_b128 v174, v[26:29]
	ds_read_b128 v[28:31], v175
	ds_read_b128 v[160:163], v175 offset:1024
	ds_write_b128 v173, v[22:25]
	ds_write_b128 v174, v[18:21]
	ds_read_b128 v[180:183], v175
	ds_read_b128 v[184:187], v175 offset:1024
	s_waitcnt vmcnt(12)
	v_lshlrev_b32_e32 v18, 16, v210
	v_and_b32_e32 v19, 0xffff0000, v210
	v_lshlrev_b32_e32 v20, 16, v211
	v_and_b32_e32 v21, 0xffff0000, v211
	s_waitcnt lgkmcnt(5)
	v_pk_add_f32 v[26:27], v[30:31], v[20:21]
	v_pk_add_f32 v[28:29], v[28:29], v[18:19]
	s_waitcnt vmcnt(12)
	v_lshlrev_b32_e32 v18, 16, v212
	v_and_b32_e32 v19, 0xffff0000, v212
	v_lshlrev_b32_e32 v20, 16, v213
	v_and_b32_e32 v21, 0xffff0000, v213
	s_waitcnt vmcnt(12)
	v_lshlrev_b32_e32 v24, 16, v216
	v_and_b32_e32 v25, 0xffff0000, v216
	v_lshlrev_b32_e32 v30, 16, v217
	v_and_b32_e32 v31, 0xffff0000, v217
	v_lshlrev_b32_e32 v164, 16, v214
	v_and_b32_e32 v165, 0xffff0000, v214
	v_lshlrev_b32_e32 v188, 16, v215
	v_and_b32_e32 v189, 0xffff0000, v215
	s_waitcnt lgkmcnt(4)
	v_pk_add_f32 v[20:21], v[162:163], v[20:21]
	v_pk_add_f32 v[22:23], v[160:161], v[18:19]
	s_waitcnt lgkmcnt(1)
	v_pk_add_f32 v[30:31], v[182:183], v[30:31]
	v_pk_add_f32 v[32:33], v[180:181], v[24:25]
	s_waitcnt lgkmcnt(0)
	v_pk_add_f32 v[18:19], v[186:187], v[188:189]
	v_pk_add_f32 v[24:25], v[184:185], v[164:165]
	v_mul_f32_e32 v179, v29, v29
	v_mul_f32_e32 v190, v27, v27
	v_mul_f32_e32 v160, v23, v23
	v_mul_f32_e32 v161, v21, v21
	v_mul_f32_e32 v162, v33, v33
	v_mul_f32_e32 v163, v31, v31
	v_mul_f32_e32 v164, v25, v25
	v_mul_f32_e32 v165, v19, v19
	v_fmac_f32_e32 v179, v28, v28
	v_fmac_f32_e32 v190, v26, v26
	v_fmac_f32_e32 v160, v22, v22
	v_fmac_f32_e32 v161, v20, v20
	v_fmac_f32_e32 v162, v32, v32
	v_fmac_f32_e32 v163, v30, v30
	v_fmac_f32_e32 v164, v24, v24
	v_fmac_f32_e32 v165, v18, v18
	v_add_f32_e32 v179, v179, v190
	v_add_f32_e32 v160, v160, v161
	v_add_f32_e32 v161, v162, v163
	v_add_f32_e32 v162, v164, v165
	v_add_f32_e32 v161, v179, v161
	v_add_f32_e32 v160, v160, v162
	ds_bpermute_b32 v162, v176, v161
	ds_bpermute_b32 v163, v176, v160
	s_waitcnt lgkmcnt(1)
	v_add_f32_e32 v161, v161, v162
	s_waitcnt lgkmcnt(0)
	v_add_f32_e32 v162, v160, v163
	ds_bpermute_b32 v160, v177, v161
	ds_bpermute_b32 v163, v177, v162
	s_waitcnt lgkmcnt(1)
	v_add_f32_e32 v160, v161, v160
	s_waitcnt lgkmcnt(0)
	v_add_f32_e32 v161, v162, v163
	ds_bpermute_b32 v162, v178, v160
	ds_bpermute_b32 v163, v178, v161
	s_and_saveexec_b64 s[34:35], s[6:7]
	s_cbranch_execz .LBB0_1085
	s_ashr_i32 s5, s4, 31
	s_waitcnt lgkmcnt(0)
	v_add_f32_e32 v163, v161, v163
	v_add_f32_e32 v162, v160, v162
	v_lshl_add_u64 v[160:161], s[4:5], 2, v[140:141]
	global_atomic_add_f32 v[160:161], v162, off
	global_atomic_add_f32 v[160:161], v163, off offset:32
.LBB0_1085:
	s_or_b64 exec, exec, s[34:35]
	s_add_i32 s4, s30, 0xb0
	v_or_b32_e32 v160, s4, v166
	v_ashrrev_i32_e32 v161, 31, v160
	s_waitcnt lgkmcnt(0)
	v_lshlrev_b64 v[162:163], 11, v[160:161]
	v_or_b32_e32 v160, 8, v160
	v_ashrrev_i32_e32 v161, 31, v160
	v_lshl_add_u64 v[162:163], s[46:47], 0, v[162:163]
	v_lshlrev_b64 v[160:161], 11, v[160:161]
	v_lshl_add_u64 v[162:163], v[162:163], 0, v[158:159]
	v_lshl_add_u64 v[160:161], s[46:47], 0, v[160:161]
	v_lshl_add_u64 v[158:159], v[160:161], 0, v[158:159]
	s_nop 0
	ds_write_b128 v173, v[14:17]
	ds_write_b128 v174, v[10:13]
	ds_read_b128 v[10:13], v175
	ds_read_b128 v[14:17], v175 offset:1024
	ds_write_b128 v173, v[6:9]
	ds_write_b128 v174, v[2:5]
	ds_read_b128 v[2:5], v175
	ds_read_b128 v[6:9], v175 offset:1024
	s_waitcnt vmcnt(8)
	v_lshlrev_b32_e32 v160, 16, v218
	v_and_b32_e32 v161, 0xffff0000, v218
	v_lshlrev_b32_e32 v158, 16, v219
	v_and_b32_e32 v159, 0xffff0000, v219
	s_waitcnt lgkmcnt(5)
	v_pk_add_f32 v[158:159], v[12:13], v[158:159]
	v_pk_add_f32 v[160:161], v[10:11], v[160:161]
	s_waitcnt vmcnt(8)
	v_lshlrev_b32_e32 v10, 16, v220
	v_and_b32_e32 v11, 0xffff0000, v220
	v_lshlrev_b32_e32 v12, 16, v221
	v_and_b32_e32 v13, 0xffff0000, v221
	s_waitcnt vmcnt(8)
	v_lshlrev_b32_e32 v164, 16, v224
	v_and_b32_e32 v165, 0xffff0000, v224
	v_lshlrev_b32_e32 v162, 16, v225
	v_and_b32_e32 v163, 0xffff0000, v225
	v_lshlrev_b32_e32 v180, 16, v222
	v_and_b32_e32 v181, 0xffff0000, v222
	v_lshlrev_b32_e32 v182, 16, v223
	v_and_b32_e32 v183, 0xffff0000, v223
	s_waitcnt lgkmcnt(4)
	v_pk_add_f32 v[12:13], v[16:17], v[12:13]
	v_pk_add_f32 v[14:15], v[14:15], v[10:11]
	s_waitcnt lgkmcnt(1)
	v_pk_add_f32 v[162:163], v[4:5], v[162:163]
	v_pk_add_f32 v[164:165], v[2:3], v[164:165]
	s_waitcnt lgkmcnt(0)
	v_pk_add_f32 v[10:11], v[8:9], v[182:183]
	v_pk_add_f32 v[16:17], v[6:7], v[180:181]
	v_mul_f32_e32 v179, v161, v161
	v_mul_f32_e32 v184, v159, v159
	v_mul_f32_e32 v2, v15, v15
	v_mul_f32_e32 v3, v13, v13
	v_mul_f32_e32 v4, v165, v165
	v_mul_f32_e32 v5, v163, v163
	v_mul_f32_e32 v6, v17, v17
	v_mul_f32_e32 v7, v11, v11
	v_fmac_f32_e32 v179, v160, v160
	v_fmac_f32_e32 v184, v158, v158
	v_fmac_f32_e32 v2, v14, v14
	v_fmac_f32_e32 v3, v12, v12
	v_fmac_f32_e32 v4, v164, v164
	v_fmac_f32_e32 v5, v162, v162
	v_fmac_f32_e32 v6, v16, v16
	v_fmac_f32_e32 v7, v10, v10
	v_add_f32_e32 v8, v179, v184
	v_add_f32_e32 v2, v2, v3
	v_add_f32_e32 v3, v4, v5
	v_add_f32_e32 v4, v6, v7
	v_add_f32_e32 v3, v8, v3
	v_add_f32_e32 v2, v2, v4
	ds_bpermute_b32 v4, v176, v3
	ds_bpermute_b32 v5, v176, v2
	s_waitcnt lgkmcnt(1)
	v_add_f32_e32 v3, v3, v4
	s_waitcnt lgkmcnt(0)
	v_add_f32_e32 v4, v2, v5
	ds_bpermute_b32 v2, v177, v3
	ds_bpermute_b32 v5, v177, v4
	s_waitcnt lgkmcnt(1)
	v_add_f32_e32 v2, v3, v2
	s_waitcnt lgkmcnt(0)
	v_add_f32_e32 v3, v4, v5
	ds_bpermute_b32 v4, v178, v2
	ds_bpermute_b32 v5, v178, v3
	s_and_saveexec_b64 s[30:31], s[6:7]
	s_cbranch_execz .LBB0_1087
	s_ashr_i32 s5, s4, 31
	s_waitcnt lgkmcnt(0)
	v_add_f32_e32 v5, v3, v5
	v_add_f32_e32 v4, v2, v4
	v_lshl_add_u64 v[2:3], s[4:5], 2, v[140:141]
	global_atomic_add_f32 v[2:3], v4, off
	global_atomic_add_f32 v[2:3], v5, off offset:32
